# rstd precompute at GEMM phase start: loads of all three passes issued up front, one wait (gu and odd in-proj)
# speedup vs baseline: 1.0284x; 1.0284x over previous
; DI float row_rstd(const float* ssq, int row) { const f32x4* q = (const f32x4*)(ssq + (size_t)row * 16); const f32x4 a = q[0] + q[1] + q[2] + q[3]; return rsqrtf((a[0] + a[1] + a[2] + a[3]) * (1.f / 1024.f) + 1e-5f); }
;   DI bool next(int i, Unit& u) const {
;     const long L = (long)i * G + c; if (L >= nwg) return false;
;     int wgid = (int)L; { const int q = nwg / NXCD, r = nwg % NXCD, xcd = wgid % NXCD, off = wgid / NXCD; wgid = (xcd < r ? xcd * (q + 1) : r * (q + 1) + (xcd - r) * q) + off; }
;     const int nig = WGM * nN, gid = wgid / nig, fm = gid * WGM, gsz = (nM - fm) < WGM ? (nM - fm) : WGM;
;     u.pm = fm + ((wgid % nig) % gsz); u.pn = (wgid % nig) / gsz; return true;
;   }
; template <class Epi>
; DI void gemm_run(const bf16_t* A, int lda, const bf16_t* Bt, int K, int N, char* lds, const Epi& e) {
;     ...
;     for (int i = tq >> 8; S.next(i, u); i += 2) sRall[i * 256 + (tq & 255)] = pg8::row_rstd(e.ssq, u.pm * 256 + (tq & 255));
.LBB0_40:
	s_and_b64 vcc, exec, s[30:31]
	s_cbranch_vccz .LBB0_808
	v_readlane_b32 s30, v252, 4
	v_readlane_b32 s31, v252, 5
	v_mov_b32_e32 v0, v200
	s_load_dword s44, s[30:31], 0x0
	s_waitcnt lgkmcnt(0)
	s_ashr_i32 s45, s44, 31
	s_waitcnt vmcnt(4)
	v_ashrrev_i32_e32 v5, 8, v0
	v_and_b32_e32 v0, 0xff, v0
	s_waitcnt vmcnt(0)
	v_lshlrev_b32_e32 v2, 2, v0
	v_lshl_or_b32 v2, v5, 10, v2
	v_add_u32_e32 v4, s33, v2
	v_mov_b64_e32 v[2:3], s[2:3]
	v_mad_i64_i32 v[2:3], s[30:31], s44, v5, v[2:3]
	s_lshl_b64 s[40:41], s[44:45], 1
	s_mov_b64 s[30:31], 0
	v_mov_b32_e32 v59, 0x57f
	v_cmp_gt_u32_e32 vcc, 0x580, v2
	s_nop 1
	v_cndmask_b32_e32 v58, v59, v2, vcc
	v_ashrrev_i32_e32 v61, 31, v58
	v_lshrrev_b32_e32 v61, 29, v61
	v_add_u32_e32 v61, v58, v61
	v_ashrrev_i32_e32 v62, 3, v61
	v_and_b32_e32 v61, -8, v61
	v_sub_u32_e32 v61, v58, v61
	v_cmp_gt_i32_e32 vcc, 0, v61
	v_mov_b32_e32 v63, 0xb0
	v_mov_b32_e32 v64, 0xb1
	v_cndmask_b32_e32 v63, v63, v64, vcc
	v_mul_lo_u32 v61, v63, v61
	v_add_u32_e32 v61, v61, v62
	s_mov_b32 s28, 0x2e8ba2e9
	v_mul_hi_i32 v62, v61, s28
	v_lshrrev_b32_e32 v63, 31, v62
	v_ashrrev_i32_e32 v62, 5, v62
	v_add_u32_e32 v62, v62, v63
	v_lshlrev_b32_e32 v63, 3, v62
	v_sub_u32_e32 v64, 64, v63
	v_min_i32_e32 v64, 8, v64
	v_sub_u32_e32 v65, 0, v64
	v_max_i32_e32 v64, v64, v65
	v_cvt_f32_u32_e32 v65, v64
	s_movk_i32 s28, 0xb0
	v_mul_lo_u32 v62, v62, s28
	v_sub_u32_e32 v61, v61, v62
	v_rcp_iflag_f32_e32 v65, v65
	v_sub_u32_e32 v66, 0, v61
	v_ashrrev_i32_e32 v62, 31, v61
	v_max_i32_e32 v61, v61, v66
	v_mul_f32_e32 v65, 0x4f7ffffe, v65
	v_cvt_u32_f32_e32 v65, v65
	v_sub_u32_e32 v66, 0, v64
	s_mov_b32 s4, 0x800000
	v_mul_lo_u32 v66, v66, v65
	v_mul_hi_u32 v66, v65, v66
	v_add_u32_e32 v65, v65, v66
	v_mul_hi_u32 v65, v61, v65
	v_mul_lo_u32 v65, v65, v64
	v_sub_u32_e32 v61, v61, v65
	v_sub_u32_e32 v65, v61, v64
	v_cmp_ge_u32_e32 vcc, v61, v64
	s_nop 0
	v_cndmask_b32_e32 v61, v61, v65, vcc
	v_sub_u32_e32 v65, v61, v64
	v_cmp_ge_u32_e32 vcc, v61, v64
	s_nop 1
	v_cndmask_b32_e32 v61, v61, v65, vcc
	v_xor_b32_e32 v61, v61, v62
	v_sub_u32_e32 v61, v61, v62
	v_add_u32_e32 v61, v61, v63
	v_lshl_or_b32 v62, v61, 8, v0
	v_ashrrev_i32_e32 v63, 31, v62
	v_lshlrev_b64 v[62:63], 6, v[62:63]
	v_lshl_add_u64 v[68:69], s[92:93], 0, v[62:63]
	global_load_dwordx4 v[76:79], v[68:69], off
	global_load_dwordx4 v[80:83], v[68:69], off offset:16
	global_load_dwordx4 v[84:87], v[68:69], off offset:32
	global_load_dwordx4 v[88:91], v[68:69], off offset:48
	v_lshl_add_u64 v[2:3], v[2:3], 0, s[40:41]
	v_cmp_gt_u32_e32 vcc, 0x580, v2
	s_nop 1
	v_cndmask_b32_e32 v58, v59, v2, vcc
	v_ashrrev_i32_e32 v61, 31, v58
	v_lshrrev_b32_e32 v61, 29, v61
	v_add_u32_e32 v61, v58, v61
	v_ashrrev_i32_e32 v62, 3, v61
	v_and_b32_e32 v61, -8, v61
	v_sub_u32_e32 v61, v58, v61
	v_cmp_gt_i32_e32 vcc, 0, v61
	v_mov_b32_e32 v63, 0xb0
	v_mov_b32_e32 v64, 0xb1
	v_cndmask_b32_e32 v63, v63, v64, vcc
	v_mul_lo_u32 v61, v63, v61
	v_add_u32_e32 v61, v61, v62
	s_mov_b32 s28, 0x2e8ba2e9
	v_mul_hi_i32 v62, v61, s28
	v_lshrrev_b32_e32 v63, 31, v62
	v_ashrrev_i32_e32 v62, 5, v62
	v_add_u32_e32 v62, v62, v63
	v_lshlrev_b32_e32 v63, 3, v62
	v_sub_u32_e32 v64, 64, v63
	v_min_i32_e32 v64, 8, v64
	v_sub_u32_e32 v65, 0, v64
	v_max_i32_e32 v64, v64, v65
	v_cvt_f32_u32_e32 v65, v64
	s_movk_i32 s28, 0xb0
	v_mul_lo_u32 v62, v62, s28
	v_sub_u32_e32 v61, v61, v62
	v_rcp_iflag_f32_e32 v65, v65
	v_sub_u32_e32 v66, 0, v61
	v_ashrrev_i32_e32 v62, 31, v61
	v_max_i32_e32 v61, v61, v66
	v_mul_f32_e32 v65, 0x4f7ffffe, v65
	v_cvt_u32_f32_e32 v65, v65
	v_sub_u32_e32 v66, 0, v64
	s_mov_b32 s4, 0x800000
	v_mul_lo_u32 v66, v66, v65
	v_mul_hi_u32 v66, v65, v66
	v_add_u32_e32 v65, v65, v66
	v_mul_hi_u32 v65, v61, v65
	v_mul_lo_u32 v65, v65, v64
	v_sub_u32_e32 v61, v61, v65
	v_sub_u32_e32 v65, v61, v64
	v_cmp_ge_u32_e32 vcc, v61, v64
	s_nop 0
	v_cndmask_b32_e32 v61, v61, v65, vcc
	v_sub_u32_e32 v65, v61, v64
	v_cmp_ge_u32_e32 vcc, v61, v64
	s_nop 1
	v_cndmask_b32_e32 v61, v61, v65, vcc
	v_xor_b32_e32 v61, v61, v62
	v_sub_u32_e32 v61, v61, v62
	v_add_u32_e32 v61, v61, v63
	v_lshl_or_b32 v62, v61, 8, v0
	v_ashrrev_i32_e32 v63, 31, v62
	v_lshlrev_b64 v[62:63], 6, v[62:63]
	v_lshl_add_u64 v[70:71], s[92:93], 0, v[62:63]
	global_load_dwordx4 v[92:95], v[70:71], off
	global_load_dwordx4 v[96:99], v[70:71], off offset:16
	global_load_dwordx4 v[100:103], v[70:71], off offset:32
	global_load_dwordx4 v[104:107], v[70:71], off offset:48
	v_lshl_add_u64 v[2:3], v[2:3], 0, s[40:41]
	v_cmp_gt_u32_e32 vcc, 0x580, v2
	s_nop 1
	v_cndmask_b32_e32 v58, v59, v2, vcc
	v_ashrrev_i32_e32 v61, 31, v58
	v_lshrrev_b32_e32 v61, 29, v61
	v_add_u32_e32 v61, v58, v61
	v_ashrrev_i32_e32 v62, 3, v61
	v_and_b32_e32 v61, -8, v61
	v_sub_u32_e32 v61, v58, v61
	v_cmp_gt_i32_e32 vcc, 0, v61
	v_mov_b32_e32 v63, 0xb0
	v_mov_b32_e32 v64, 0xb1
	v_cndmask_b32_e32 v63, v63, v64, vcc
	v_mul_lo_u32 v61, v63, v61
	v_add_u32_e32 v61, v61, v62
	s_mov_b32 s28, 0x2e8ba2e9
	v_mul_hi_i32 v62, v61, s28
	v_lshrrev_b32_e32 v63, 31, v62
	v_ashrrev_i32_e32 v62, 5, v62
	v_add_u32_e32 v62, v62, v63
	v_lshlrev_b32_e32 v63, 3, v62
	v_sub_u32_e32 v64, 64, v63
	v_min_i32_e32 v64, 8, v64
	v_sub_u32_e32 v65, 0, v64
	v_max_i32_e32 v64, v64, v65
	v_cvt_f32_u32_e32 v65, v64
	s_movk_i32 s28, 0xb0
	v_mul_lo_u32 v62, v62, s28
	v_sub_u32_e32 v61, v61, v62
	v_rcp_iflag_f32_e32 v65, v65
	v_sub_u32_e32 v66, 0, v61
	v_ashrrev_i32_e32 v62, 31, v61
	v_max_i32_e32 v61, v61, v66
	v_mul_f32_e32 v65, 0x4f7ffffe, v65
	v_cvt_u32_f32_e32 v65, v65
	v_sub_u32_e32 v66, 0, v64
	s_mov_b32 s4, 0x800000
	v_mul_lo_u32 v66, v66, v65
	v_mul_hi_u32 v66, v65, v66
	v_add_u32_e32 v65, v65, v66
	v_mul_hi_u32 v65, v61, v65
	v_mul_lo_u32 v65, v65, v64
	v_sub_u32_e32 v61, v61, v65
	v_sub_u32_e32 v65, v61, v64
	v_cmp_ge_u32_e32 vcc, v61, v64
	s_nop 0
	v_cndmask_b32_e32 v61, v61, v65, vcc
	v_sub_u32_e32 v65, v61, v64
	v_cmp_ge_u32_e32 vcc, v61, v64
	s_nop 1
	v_cndmask_b32_e32 v61, v61, v65, vcc
	v_xor_b32_e32 v61, v61, v62
	v_sub_u32_e32 v61, v61, v62
	v_add_u32_e32 v61, v61, v63
	v_lshl_or_b32 v62, v61, 8, v0
	v_ashrrev_i32_e32 v63, 31, v62
	v_lshlrev_b64 v[62:63], 6, v[62:63]
	v_lshl_add_u64 v[72:73], s[92:93], 0, v[62:63]
	global_load_dwordx4 v[108:111], v[72:73], off
	global_load_dwordx4 v[112:115], v[72:73], off offset:16
	global_load_dwordx4 v[116:119], v[72:73], off offset:32
	global_load_dwordx4 v[120:123], v[72:73], off offset:48
	v_lshl_add_u64 v[2:3], v[2:3], 0, s[40:41]
	s_waitcnt vmcnt(0)
; DI float row_rstd(const float* ssq, int row) { const f32x4* q = (const f32x4*)(ssq + (size_t)row * 16); const f32x4 a = q[0] + q[1] + q[2] + q[3]; return rsqrtf((a[0] + a[1] + a[2] + a[3]) * (1.f / 1024.f) + 1e-5f); }
; template <class Epi>
; DI void gemm_run(const bf16_t* A, int lda, const bf16_t* Bt, int K, int N, char* lds, const Epi& e) {
;     ...
;     for (int i = tq >> 8; S.next(i, u); i += 2) sRall[i * 256 + (tq & 255)] = pg8::row_rstd(e.ssq, u.pm * 256 + (tq & 255));
	v_pk_add_f32 v[76:77], v[76:77], v[80:81]
	v_pk_add_f32 v[78:79], v[78:79], v[82:83]
	v_pk_add_f32 v[76:77], v[76:77], v[84:85]
	v_pk_add_f32 v[78:79], v[78:79], v[86:87]
	v_pk_add_f32 v[76:77], v[76:77], v[88:89]
	v_pk_add_f32 v[78:79], v[78:79], v[90:91]
	v_add_f32_e32 v61, v76, v77
	v_add_f32_e32 v61, v78, v61
	v_add_f32_e32 v61, v79, v61
	v_fmamk_f32 v61, v61, 0x3a800000, v201
	v_mul_f32_e32 v76, 0x4b800000, v61
	v_cmp_gt_f32_e32 vcc, s4, v61
	s_nop 1
	v_cndmask_b32_e32 v61, v61, v76, vcc
	v_rsq_f32_e32 v61, v61
	s_nop 0
	v_mul_f32_e32 v76, 0x45800000, v61
	v_cndmask_b32_e32 v61, v61, v76, vcc
	ds_write_b32 v4, v61
	v_pk_add_f32 v[92:93], v[92:93], v[96:97]
	v_pk_add_f32 v[94:95], v[94:95], v[98:99]
	v_pk_add_f32 v[92:93], v[92:93], v[100:101]
	v_pk_add_f32 v[94:95], v[94:95], v[102:103]
	v_pk_add_f32 v[92:93], v[92:93], v[104:105]
	v_pk_add_f32 v[94:95], v[94:95], v[106:107]
	v_add_f32_e32 v61, v92, v93
	v_add_f32_e32 v61, v94, v61
	v_add_f32_e32 v61, v95, v61
	v_fmamk_f32 v61, v61, 0x3a800000, v201
	v_mul_f32_e32 v92, 0x4b800000, v61
	v_cmp_gt_f32_e32 vcc, s4, v61
	s_nop 1
	v_cndmask_b32_e32 v61, v61, v92, vcc
	v_rsq_f32_e32 v61, v61
	s_nop 0
	v_mul_f32_e32 v92, 0x45800000, v61
	v_cndmask_b32_e32 v61, v61, v92, vcc
	ds_write_b32 v4, v61 offset:2048
	v_pk_add_f32 v[108:109], v[108:109], v[112:113]
	v_pk_add_f32 v[110:111], v[110:111], v[114:115]
	v_pk_add_f32 v[108:109], v[108:109], v[116:117]
	v_pk_add_f32 v[110:111], v[110:111], v[118:119]
	v_pk_add_f32 v[108:109], v[108:109], v[120:121]
	v_pk_add_f32 v[110:111], v[110:111], v[122:123]
	v_add_f32_e32 v61, v108, v109
	v_add_f32_e32 v61, v110, v61
	v_add_f32_e32 v61, v111, v61
	v_fmamk_f32 v61, v61, 0x3a800000, v201
	v_mul_f32_e32 v108, 0x4b800000, v61
	v_cmp_gt_f32_e32 vcc, s4, v61
	s_nop 1
	v_cndmask_b32_e32 v61, v61, v108, vcc
	v_rsq_f32_e32 v61, v61
	s_nop 0
	v_mul_f32_e32 v108, 0x45800000, v61
	v_cndmask_b32_e32 v61, v61, v108, vcc
	ds_write_b32 v4, v61 offset:4096
	v_add_u32_e32 v4, 0x1800, v4
	s_branch .LBB0_43

; DI float row_rstd(const float* ssq, int row) { const f32x4* q = (const f32x4*)(ssq + (size_t)row * 16); const f32x4 a = q[0] + q[1] + q[2] + q[3]; return rsqrtf((a[0] + a[1] + a[2] + a[3]) * (1.f / 1024.f) + 1e-5f); }
;   DI bool next(int i, Unit& u) const {
;     const long L = (long)i * G + c; if (L >= nwg) return false;
;     int wgid = (int)L; { const int q = nwg / NXCD, r = nwg % NXCD, xcd = wgid % NXCD, off = wgid / NXCD; wgid = (xcd < r ? xcd * (q + 1) : r * (q + 1) + (xcd - r) * q) + off; }
;     const int nig = WGM * nN, gid = wgid / nig, fm = gid * WGM, gsz = (nM - fm) < WGM ? (nM - fm) : WGM;
;     u.pm = fm + ((wgid % nig) % gsz); u.pn = (wgid % nig) / gsz; return true;
;   }
; template <class Epi>
; DI void gemm_run(const bf16_t* A, int lda, const bf16_t* Bt, int K, int N, char* lds, const Epi& e) {
;     ...
;     for (int i = tq >> 8; S.next(i, u); i += 2) sRall[i * 256 + (tq & 255)] = pg8::row_rstd(e.ssq, u.pm * 256 + (tq & 255));
.LBB0_1160:
	v_readlane_b32 s0, v255, 21
	v_readlane_b32 s1, v255, 22
	s_andn2_b64 vcc, exec, s[0:1]
	s_movk_i32 s80, 0x3fff
	s_cbranch_vccnz .LBB0_2038
	v_readlane_b32 s0, v255, 23
	s_cmp_gt_i32 s0, 0
	s_mov_b64 s[0:1], -1
	s_cbranch_scc0 .LBB0_1502
	v_readlane_b32 s4, v255, 19
	v_readlane_b32 s5, v255, 20
	s_and_b64 vcc, exec, s[4:5]
	s_cbranch_vccz .LBB0_1185
	v_readlane_b32 s0, v252, 4
	v_readlane_b32 s1, v252, 5
	v_mov_b32_e32 v0, v200
	s_load_dword s0, s[0:1], 0x0
	s_waitcnt lgkmcnt(0)
	s_ashr_i32 s1, s0, 31
	s_waitcnt vmcnt(4)
	v_ashrrev_i32_e32 v5, 8, v0
	v_and_b32_e32 v0, 0xff, v0
	s_waitcnt vmcnt(0)
	v_lshlrev_b32_e32 v2, 2, v0
	v_lshl_or_b32 v2, v5, 10, v2
	v_add_u32_e32 v4, s33, v2
	v_mov_b64_e32 v[2:3], s[2:3]
	v_mad_i64_i32 v[2:3], s[30:31], s0, v5, v[2:3]
	s_lshl_b64 s[40:41], s[0:1], 1
	s_mov_b64 s[30:31], 0
	v_mov_b32_e32 v59, 0x53f
	v_cmp_gt_u32_e32 vcc, 0x540, v2
	s_nop 1
	v_cndmask_b32_e32 v58, v59, v2, vcc
	v_ashrrev_i32_e32 v61, 31, v58
	v_lshrrev_b32_e32 v61, 29, v61
	v_add_u32_e32 v61, v58, v61
	v_ashrrev_i32_e32 v62, 3, v61
	v_and_b32_e32 v61, -8, v61
	v_sub_u32_e32 v61, v58, v61
	v_lshrrev_b32_e32 v63, 31, v61
	v_or_b32_e32 v63, 0xa8, v63
	v_mul_lo_u32 v61, v63, v61
	v_add_u32_e32 v61, v61, v62
	s_mov_b32 s28, 0x30c30c31
	v_mul_hi_i32 v62, v61, s28
	v_lshrrev_b32_e32 v63, 31, v62
	v_ashrrev_i32_e32 v62, 5, v62
	v_add_u32_e32 v62, v62, v63
	v_lshlrev_b32_e32 v63, 3, v62
	v_sub_u32_e32 v64, 64, v63
	v_min_i32_e32 v64, 8, v64
	v_sub_u32_e32 v65, 0, v64
	v_max_i32_e32 v64, v64, v65
	v_cvt_f32_u32_e32 v65, v64
	s_movk_i32 s28, 0xa8
	v_mul_lo_u32 v62, v62, s28
	v_sub_u32_e32 v61, v61, v62
	v_rcp_iflag_f32_e32 v65, v65
	v_sub_u32_e32 v66, 0, v61
	v_ashrrev_i32_e32 v62, 31, v61
	v_max_i32_e32 v61, v61, v66
	v_mul_f32_e32 v65, 0x4f7ffffe, v65
	v_cvt_u32_f32_e32 v65, v65
	v_sub_u32_e32 v66, 0, v64
	s_mov_b32 s4, 0x800000
	v_mul_lo_u32 v66, v66, v65
	v_mul_hi_u32 v66, v65, v66
	v_add_u32_e32 v65, v65, v66
	v_mul_hi_u32 v65, v61, v65
	v_mul_lo_u32 v65, v65, v64
	v_sub_u32_e32 v61, v61, v65
	v_sub_u32_e32 v65, v61, v64
	v_cmp_ge_u32_e32 vcc, v61, v64
	s_nop 0
	v_cndmask_b32_e32 v61, v61, v65, vcc
	v_sub_u32_e32 v65, v61, v64
	v_cmp_ge_u32_e32 vcc, v61, v64
	s_nop 1
	v_cndmask_b32_e32 v61, v61, v65, vcc
	v_xor_b32_e32 v61, v61, v62
	v_sub_u32_e32 v61, v61, v62
	v_add_u32_e32 v61, v61, v63
	v_lshl_or_b32 v62, v61, 8, v0
	v_ashrrev_i32_e32 v63, 31, v62
	v_lshlrev_b64 v[62:63], 6, v[62:63]
	v_lshl_add_u64 v[68:69], s[92:93], 0, v[62:63]
	global_load_dwordx4 v[76:79], v[68:69], off
	global_load_dwordx4 v[80:83], v[68:69], off offset:16
	global_load_dwordx4 v[84:87], v[68:69], off offset:32
	global_load_dwordx4 v[88:91], v[68:69], off offset:48
	v_lshl_add_u64 v[2:3], v[2:3], 0, s[40:41]
	v_cmp_gt_u32_e32 vcc, 0x540, v2
	s_nop 1
	v_cndmask_b32_e32 v58, v59, v2, vcc
	v_ashrrev_i32_e32 v61, 31, v58
	v_lshrrev_b32_e32 v61, 29, v61
	v_add_u32_e32 v61, v58, v61
	v_ashrrev_i32_e32 v62, 3, v61
	v_and_b32_e32 v61, -8, v61
	v_sub_u32_e32 v61, v58, v61
	v_lshrrev_b32_e32 v63, 31, v61
	v_or_b32_e32 v63, 0xa8, v63
	v_mul_lo_u32 v61, v63, v61
	v_add_u32_e32 v61, v61, v62
	s_mov_b32 s28, 0x30c30c31
	v_mul_hi_i32 v62, v61, s28
	v_lshrrev_b32_e32 v63, 31, v62
	v_ashrrev_i32_e32 v62, 5, v62
	v_add_u32_e32 v62, v62, v63
	v_lshlrev_b32_e32 v63, 3, v62
	v_sub_u32_e32 v64, 64, v63
	v_min_i32_e32 v64, 8, v64
	v_sub_u32_e32 v65, 0, v64
	v_max_i32_e32 v64, v64, v65
	v_cvt_f32_u32_e32 v65, v64
	s_movk_i32 s28, 0xa8
	v_mul_lo_u32 v62, v62, s28
	v_sub_u32_e32 v61, v61, v62
	v_rcp_iflag_f32_e32 v65, v65
	v_sub_u32_e32 v66, 0, v61
	v_ashrrev_i32_e32 v62, 31, v61
	v_max_i32_e32 v61, v61, v66
	v_mul_f32_e32 v65, 0x4f7ffffe, v65
	v_cvt_u32_f32_e32 v65, v65
	v_sub_u32_e32 v66, 0, v64
	s_mov_b32 s4, 0x800000
	v_mul_lo_u32 v66, v66, v65
	v_mul_hi_u32 v66, v65, v66
	v_add_u32_e32 v65, v65, v66
	v_mul_hi_u32 v65, v61, v65
	v_mul_lo_u32 v65, v65, v64
	v_sub_u32_e32 v61, v61, v65
	v_sub_u32_e32 v65, v61, v64
	v_cmp_ge_u32_e32 vcc, v61, v64
	s_nop 0
	v_cndmask_b32_e32 v61, v61, v65, vcc
	v_sub_u32_e32 v65, v61, v64
	v_cmp_ge_u32_e32 vcc, v61, v64
	s_nop 1
	v_cndmask_b32_e32 v61, v61, v65, vcc
	v_xor_b32_e32 v61, v61, v62
	v_sub_u32_e32 v61, v61, v62
	v_add_u32_e32 v61, v61, v63
	v_lshl_or_b32 v62, v61, 8, v0
	v_ashrrev_i32_e32 v63, 31, v62
	v_lshlrev_b64 v[62:63], 6, v[62:63]
	v_lshl_add_u64 v[70:71], s[92:93], 0, v[62:63]
	global_load_dwordx4 v[92:95], v[70:71], off
	global_load_dwordx4 v[96:99], v[70:71], off offset:16
	global_load_dwordx4 v[100:103], v[70:71], off offset:32
	global_load_dwordx4 v[104:107], v[70:71], off offset:48
	v_lshl_add_u64 v[2:3], v[2:3], 0, s[40:41]
	v_cmp_gt_u32_e32 vcc, 0x540, v2
	s_nop 1
	v_cndmask_b32_e32 v58, v59, v2, vcc
	v_ashrrev_i32_e32 v61, 31, v58
	v_lshrrev_b32_e32 v61, 29, v61
	v_add_u32_e32 v61, v58, v61
	v_ashrrev_i32_e32 v62, 3, v61
	v_and_b32_e32 v61, -8, v61
	v_sub_u32_e32 v61, v58, v61
	v_lshrrev_b32_e32 v63, 31, v61
	v_or_b32_e32 v63, 0xa8, v63
	v_mul_lo_u32 v61, v63, v61
	v_add_u32_e32 v61, v61, v62
	s_mov_b32 s28, 0x30c30c31
	v_mul_hi_i32 v62, v61, s28
	v_lshrrev_b32_e32 v63, 31, v62
	v_ashrrev_i32_e32 v62, 5, v62
	v_add_u32_e32 v62, v62, v63
	v_lshlrev_b32_e32 v63, 3, v62
	v_sub_u32_e32 v64, 64, v63
	v_min_i32_e32 v64, 8, v64
	v_sub_u32_e32 v65, 0, v64
	v_max_i32_e32 v64, v64, v65
	v_cvt_f32_u32_e32 v65, v64
	s_movk_i32 s28, 0xa8
	v_mul_lo_u32 v62, v62, s28
	v_sub_u32_e32 v61, v61, v62
	v_rcp_iflag_f32_e32 v65, v65
	v_sub_u32_e32 v66, 0, v61
	v_ashrrev_i32_e32 v62, 31, v61
	v_max_i32_e32 v61, v61, v66
	v_mul_f32_e32 v65, 0x4f7ffffe, v65
	v_cvt_u32_f32_e32 v65, v65
	v_sub_u32_e32 v66, 0, v64
	s_mov_b32 s4, 0x800000
	v_mul_lo_u32 v66, v66, v65
	v_mul_hi_u32 v66, v65, v66
	v_add_u32_e32 v65, v65, v66
	v_mul_hi_u32 v65, v61, v65
	v_mul_lo_u32 v65, v65, v64
	v_sub_u32_e32 v61, v61, v65
	v_sub_u32_e32 v65, v61, v64
	v_cmp_ge_u32_e32 vcc, v61, v64
	s_nop 0
	v_cndmask_b32_e32 v61, v61, v65, vcc
	v_sub_u32_e32 v65, v61, v64
	v_cmp_ge_u32_e32 vcc, v61, v64
	s_nop 1
	v_cndmask_b32_e32 v61, v61, v65, vcc
	v_xor_b32_e32 v61, v61, v62
	v_sub_u32_e32 v61, v61, v62
	v_add_u32_e32 v61, v61, v63
	v_lshl_or_b32 v62, v61, 8, v0
	v_ashrrev_i32_e32 v63, 31, v62
	v_lshlrev_b64 v[62:63], 6, v[62:63]
	v_lshl_add_u64 v[72:73], s[92:93], 0, v[62:63]
	global_load_dwordx4 v[108:111], v[72:73], off
	global_load_dwordx4 v[112:115], v[72:73], off offset:16
	global_load_dwordx4 v[116:119], v[72:73], off offset:32
	global_load_dwordx4 v[120:123], v[72:73], off offset:48
	v_lshl_add_u64 v[2:3], v[2:3], 0, s[40:41]
	s_waitcnt vmcnt(0)
; DI float row_rstd(const float* ssq, int row) { const f32x4* q = (const f32x4*)(ssq + (size_t)row * 16); const f32x4 a = q[0] + q[1] + q[2] + q[3]; return rsqrtf((a[0] + a[1] + a[2] + a[3]) * (1.f / 1024.f) + 1e-5f); }
; template <class Epi>
; DI void gemm_run(const bf16_t* A, int lda, const bf16_t* Bt, int K, int N, char* lds, const Epi& e) {
;     ...
;     for (int i = tq >> 8; S.next(i, u); i += 2) sRall[i * 256 + (tq & 255)] = pg8::row_rstd(e.ssq, u.pm * 256 + (tq & 255));
	v_pk_add_f32 v[76:77], v[76:77], v[80:81]
	v_pk_add_f32 v[78:79], v[78:79], v[82:83]
	v_pk_add_f32 v[76:77], v[76:77], v[84:85]
	v_pk_add_f32 v[78:79], v[78:79], v[86:87]
	v_pk_add_f32 v[76:77], v[76:77], v[88:89]
	v_pk_add_f32 v[78:79], v[78:79], v[90:91]
	v_add_f32_e32 v61, v76, v77
	v_add_f32_e32 v61, v78, v61
	v_add_f32_e32 v61, v79, v61
	v_fmamk_f32 v61, v61, 0x3a800000, v201
	v_mul_f32_e32 v76, 0x4b800000, v61
	v_cmp_gt_f32_e32 vcc, s4, v61
	s_nop 1
	v_cndmask_b32_e32 v61, v61, v76, vcc
	v_rsq_f32_e32 v61, v61
	s_nop 0
	v_mul_f32_e32 v76, 0x45800000, v61
	v_cndmask_b32_e32 v61, v61, v76, vcc
	ds_write_b32 v4, v61
	v_pk_add_f32 v[92:93], v[92:93], v[96:97]
	v_pk_add_f32 v[94:95], v[94:95], v[98:99]
	v_pk_add_f32 v[92:93], v[92:93], v[100:101]
	v_pk_add_f32 v[94:95], v[94:95], v[102:103]
	v_pk_add_f32 v[92:93], v[92:93], v[104:105]
	v_pk_add_f32 v[94:95], v[94:95], v[106:107]
	v_add_f32_e32 v61, v92, v93
	v_add_f32_e32 v61, v94, v61
	v_add_f32_e32 v61, v95, v61
	v_fmamk_f32 v61, v61, 0x3a800000, v201
	v_mul_f32_e32 v92, 0x4b800000, v61
	v_cmp_gt_f32_e32 vcc, s4, v61
	s_nop 1
	v_cndmask_b32_e32 v61, v61, v92, vcc
	v_rsq_f32_e32 v61, v61
	s_nop 0
	v_mul_f32_e32 v92, 0x45800000, v61
	v_cndmask_b32_e32 v61, v61, v92, vcc
	ds_write_b32 v4, v61 offset:2048
	v_pk_add_f32 v[108:109], v[108:109], v[112:113]
	v_pk_add_f32 v[110:111], v[110:111], v[114:115]
	v_pk_add_f32 v[108:109], v[108:109], v[116:117]
	v_pk_add_f32 v[110:111], v[110:111], v[118:119]
	v_pk_add_f32 v[108:109], v[108:109], v[120:121]
	v_pk_add_f32 v[110:111], v[110:111], v[122:123]
	v_add_f32_e32 v61, v108, v109
	v_add_f32_e32 v61, v110, v61
	v_add_f32_e32 v61, v111, v61
	v_fmamk_f32 v61, v61, 0x3a800000, v201
	v_mul_f32_e32 v108, 0x4b800000, v61
	v_cmp_gt_f32_e32 vcc, s4, v61
	s_nop 1
	v_cndmask_b32_e32 v61, v61, v108, vcc
	v_rsq_f32_e32 v61, v61
	s_nop 0
	v_mul_f32_e32 v108, 0x45800000, v61
	v_cndmask_b32_e32 v61, v61, v108, vcc
	ds_write_b32 v4, v61 offset:4096
	v_add_u32_e32 v4, 0x1800, v4
	s_branch .LBB0_1165
